# band epilogue: pairs of 8-byte pieces exchanged with v_permlane16_swap and stored as dwordx4 (16 stores per lane become 8)
# baseline (speedup 1.0000x reference)
.Lband_epi_compute:
	v_bfe_u32 v246, v124, 3, 1
	v_mul_u32_u24_e32 v246, 24, v246
	v_add_u32_e32 v244, v124, v246
	v_add_u32_e32 v245, 0x10000, v244
	v_rcp_f32_e32 v118, v126
	v_rcp_f32_e32 v119, v34
	s_nop 0
	v_fma_f32 v0, -v126, v118, 1.0
	v_fma_f32 v120, -v34, v119, 1.0
	v_fmac_f32_e32 v118, v0, v118
	v_fmac_f32_e32 v119, v120, v119
	v_mov_b32_e32 v0, v118
	v_mov_b32_e32 v120, v119
	s_waitcnt vmcnt(15)
	v_lshlrev_b32_e32 v66, 16, v86
	v_and_b32_e32 v67, 0xffff0000, v86
	v_lshlrev_b32_e32 v68, 16, v87
	v_and_b32_e32 v69, 0xffff0000, v87
	v_mul_f32_e32 v70, 0xbfb8aa3b, v66
	v_mul_f32_e32 v71, 0xbfb8aa3b, v67
	v_mul_f32_e32 v72, 0xbfb8aa3b, v68
	v_mul_f32_e32 v73, 0xbfb8aa3b, v69
	v_exp_f32_e32 v70, v70
	v_exp_f32_e32 v71, v71
	v_exp_f32_e32 v72, v72
	v_exp_f32_e32 v73, v73
	v_pk_mul_f32 v[78:79], v[82:83], v[0:1] op_sel_hi:[1,0]
	v_pk_add_f32 v[70:71], v[70:71], 1.0 op_sel_hi:[1,0]
	v_pk_add_f32 v[72:73], v[72:73], 1.0 op_sel_hi:[1,0]
	v_rcp_f32_e32 v74, v70
	v_rcp_f32_e32 v75, v71
	v_rcp_f32_e32 v76, v72
	v_rcp_f32_e32 v77, v73
	v_pk_mul_f32 v[80:81], v[84:85], v[0:1] op_sel_hi:[1,0]
	v_pk_mul_f32 v[74:75], v[66:67], v[74:75]
	v_pk_mul_f32 v[76:77], v[68:69], v[76:77]
	v_pk_mul_f32 v[78:79], v[78:79], v[74:75]
	v_pk_mul_f32 v[80:81], v[80:81], v[76:77]
	v_cvt_pk_bf16_f32 v240, v78, v79
	v_cvt_pk_bf16_f32 v241, v80, v81
	s_waitcnt vmcnt(14)
	v_lshlrev_b32_e32 v66, 16, v88
	v_and_b32_e32 v67, 0xffff0000, v88
	v_lshlrev_b32_e32 v68, 16, v89
	v_and_b32_e32 v69, 0xffff0000, v89
	v_mul_f32_e32 v70, 0xbfb8aa3b, v66
	v_mul_f32_e32 v71, 0xbfb8aa3b, v67
	v_mul_f32_e32 v72, 0xbfb8aa3b, v68
	v_mul_f32_e32 v73, 0xbfb8aa3b, v69
	v_exp_f32_e32 v70, v70
	v_exp_f32_e32 v71, v71
	v_exp_f32_e32 v72, v72
	v_exp_f32_e32 v73, v73
	v_pk_mul_f32 v[78:79], v[62:63], v[0:1] op_sel_hi:[1,0]
	v_pk_add_f32 v[70:71], v[70:71], 1.0 op_sel_hi:[1,0]
	v_pk_add_f32 v[72:73], v[72:73], 1.0 op_sel_hi:[1,0]
	v_rcp_f32_e32 v74, v70
	v_rcp_f32_e32 v75, v71
	v_rcp_f32_e32 v76, v72
	v_rcp_f32_e32 v77, v73
	v_pk_mul_f32 v[80:81], v[64:65], v[0:1] op_sel_hi:[1,0]
	v_pk_mul_f32 v[74:75], v[66:67], v[74:75]
	v_pk_mul_f32 v[76:77], v[68:69], v[76:77]
	v_pk_mul_f32 v[78:79], v[78:79], v[74:75]
	v_pk_mul_f32 v[80:81], v[80:81], v[76:77]
	v_cvt_pk_bf16_f32 v242, v78, v79
	v_cvt_pk_bf16_f32 v243, v80, v81
	s_nop 1
	v_permlane16_swap_b32_e32 v240, v242
	v_permlane16_swap_b32_e32 v241, v243
	global_store_dwordx4 v244, v[240:243], s[38:39]
	s_waitcnt vmcnt(14)
	v_lshlrev_b32_e32 v66, 16, v90
	v_and_b32_e32 v67, 0xffff0000, v90
	v_lshlrev_b32_e32 v68, 16, v91
	v_and_b32_e32 v69, 0xffff0000, v91
	v_mul_f32_e32 v70, 0xbfb8aa3b, v66
	v_mul_f32_e32 v71, 0xbfb8aa3b, v67
	v_mul_f32_e32 v72, 0xbfb8aa3b, v68
	v_mul_f32_e32 v73, 0xbfb8aa3b, v69
	v_exp_f32_e32 v70, v70
	v_exp_f32_e32 v71, v71
	v_exp_f32_e32 v72, v72
	v_exp_f32_e32 v73, v73
	v_pk_mul_f32 v[78:79], v[58:59], v[0:1] op_sel_hi:[1,0]
	v_pk_add_f32 v[70:71], v[70:71], 1.0 op_sel_hi:[1,0]
	v_pk_add_f32 v[72:73], v[72:73], 1.0 op_sel_hi:[1,0]
	v_rcp_f32_e32 v74, v70
	v_rcp_f32_e32 v75, v71
	v_rcp_f32_e32 v76, v72
	v_rcp_f32_e32 v77, v73
	v_pk_mul_f32 v[80:81], v[60:61], v[0:1] op_sel_hi:[1,0]
	v_pk_mul_f32 v[74:75], v[66:67], v[74:75]
	v_pk_mul_f32 v[76:77], v[68:69], v[76:77]
	v_pk_mul_f32 v[78:79], v[78:79], v[74:75]
	v_pk_mul_f32 v[80:81], v[80:81], v[76:77]
	v_cvt_pk_bf16_f32 v240, v78, v79
	v_cvt_pk_bf16_f32 v241, v80, v81
	s_waitcnt vmcnt(13)
	v_lshlrev_b32_e32 v66, 16, v92
	v_and_b32_e32 v67, 0xffff0000, v92
	v_lshlrev_b32_e32 v68, 16, v93
	v_and_b32_e32 v69, 0xffff0000, v93
	v_mul_f32_e32 v70, 0xbfb8aa3b, v66
	v_mul_f32_e32 v71, 0xbfb8aa3b, v67
	v_mul_f32_e32 v72, 0xbfb8aa3b, v68
	v_mul_f32_e32 v73, 0xbfb8aa3b, v69
	v_exp_f32_e32 v70, v70
	v_exp_f32_e32 v71, v71
	v_exp_f32_e32 v72, v72
	v_exp_f32_e32 v73, v73
	v_pk_mul_f32 v[78:79], v[54:55], v[0:1] op_sel_hi:[1,0]
	v_pk_add_f32 v[70:71], v[70:71], 1.0 op_sel_hi:[1,0]
	v_pk_add_f32 v[72:73], v[72:73], 1.0 op_sel_hi:[1,0]
	v_rcp_f32_e32 v74, v70
	v_rcp_f32_e32 v75, v71
	v_rcp_f32_e32 v76, v72
	v_rcp_f32_e32 v77, v73
	v_pk_mul_f32 v[80:81], v[56:57], v[0:1] op_sel_hi:[1,0]
	v_pk_mul_f32 v[74:75], v[66:67], v[74:75]
	v_pk_mul_f32 v[76:77], v[68:69], v[76:77]
	v_pk_mul_f32 v[78:79], v[78:79], v[74:75]
	v_pk_mul_f32 v[80:81], v[80:81], v[76:77]
	v_cvt_pk_bf16_f32 v242, v78, v79
	v_cvt_pk_bf16_f32 v243, v80, v81
	s_nop 1
	v_permlane16_swap_b32_e32 v240, v242
	v_permlane16_swap_b32_e32 v241, v243
	global_store_dwordx4 v244, v[240:243], s[38:39] offset:64
	s_waitcnt vmcnt(13)
	v_lshlrev_b32_e32 v66, 16, v94
	v_and_b32_e32 v67, 0xffff0000, v94
	v_lshlrev_b32_e32 v68, 16, v95
	v_and_b32_e32 v69, 0xffff0000, v95
	v_mul_f32_e32 v70, 0xbfb8aa3b, v66
	v_mul_f32_e32 v71, 0xbfb8aa3b, v67
	v_mul_f32_e32 v72, 0xbfb8aa3b, v68
	v_mul_f32_e32 v73, 0xbfb8aa3b, v69
	v_exp_f32_e32 v70, v70
	v_exp_f32_e32 v71, v71
	v_exp_f32_e32 v72, v72
	v_exp_f32_e32 v73, v73
	v_pk_mul_f32 v[78:79], v[50:51], v[0:1] op_sel_hi:[1,0]
	v_pk_add_f32 v[70:71], v[70:71], 1.0 op_sel_hi:[1,0]
	v_pk_add_f32 v[72:73], v[72:73], 1.0 op_sel_hi:[1,0]
	v_rcp_f32_e32 v74, v70
	v_rcp_f32_e32 v75, v71
	v_rcp_f32_e32 v76, v72
	v_rcp_f32_e32 v77, v73
	v_pk_mul_f32 v[80:81], v[52:53], v[0:1] op_sel_hi:[1,0]
	v_pk_mul_f32 v[74:75], v[66:67], v[74:75]
	v_pk_mul_f32 v[76:77], v[68:69], v[76:77]
	v_pk_mul_f32 v[78:79], v[78:79], v[74:75]
	v_pk_mul_f32 v[80:81], v[80:81], v[76:77]
	v_cvt_pk_bf16_f32 v240, v78, v79
	v_cvt_pk_bf16_f32 v241, v80, v81
	s_waitcnt vmcnt(12)
	v_lshlrev_b32_e32 v66, 16, v96
	v_and_b32_e32 v67, 0xffff0000, v96
	v_lshlrev_b32_e32 v68, 16, v97
	v_and_b32_e32 v69, 0xffff0000, v97
	v_mul_f32_e32 v70, 0xbfb8aa3b, v66
	v_mul_f32_e32 v71, 0xbfb8aa3b, v67
	v_mul_f32_e32 v72, 0xbfb8aa3b, v68
	v_mul_f32_e32 v73, 0xbfb8aa3b, v69
	v_exp_f32_e32 v70, v70
	v_exp_f32_e32 v71, v71
	v_exp_f32_e32 v72, v72
	v_exp_f32_e32 v73, v73
	v_pk_mul_f32 v[78:79], v[46:47], v[0:1] op_sel_hi:[1,0]
	v_pk_add_f32 v[70:71], v[70:71], 1.0 op_sel_hi:[1,0]
	v_pk_add_f32 v[72:73], v[72:73], 1.0 op_sel_hi:[1,0]
	v_rcp_f32_e32 v74, v70
	v_rcp_f32_e32 v75, v71
	v_rcp_f32_e32 v76, v72
	v_rcp_f32_e32 v77, v73
	v_pk_mul_f32 v[80:81], v[48:49], v[0:1] op_sel_hi:[1,0]
	v_pk_mul_f32 v[74:75], v[66:67], v[74:75]
	v_pk_mul_f32 v[76:77], v[68:69], v[76:77]
	v_pk_mul_f32 v[78:79], v[78:79], v[74:75]
	v_pk_mul_f32 v[80:81], v[80:81], v[76:77]
	v_cvt_pk_bf16_f32 v242, v78, v79
	v_cvt_pk_bf16_f32 v243, v80, v81
	s_nop 1
	v_permlane16_swap_b32_e32 v240, v242
	v_permlane16_swap_b32_e32 v241, v243
	global_store_dwordx4 v244, v[240:243], s[38:39] offset:128
	s_waitcnt vmcnt(12)
	v_lshlrev_b32_e32 v66, 16, v98
	v_and_b32_e32 v67, 0xffff0000, v98
	v_lshlrev_b32_e32 v68, 16, v99
	v_and_b32_e32 v69, 0xffff0000, v99
	v_mul_f32_e32 v70, 0xbfb8aa3b, v66
	v_mul_f32_e32 v71, 0xbfb8aa3b, v67
	v_mul_f32_e32 v72, 0xbfb8aa3b, v68
	v_mul_f32_e32 v73, 0xbfb8aa3b, v69
	v_exp_f32_e32 v70, v70
	v_exp_f32_e32 v71, v71
	v_exp_f32_e32 v72, v72
	v_exp_f32_e32 v73, v73
	v_pk_mul_f32 v[78:79], v[42:43], v[0:1] op_sel_hi:[1,0]
	v_pk_add_f32 v[70:71], v[70:71], 1.0 op_sel_hi:[1,0]
	v_pk_add_f32 v[72:73], v[72:73], 1.0 op_sel_hi:[1,0]
	v_rcp_f32_e32 v74, v70
	v_rcp_f32_e32 v75, v71
	v_rcp_f32_e32 v76, v72
	v_rcp_f32_e32 v77, v73
	v_pk_mul_f32 v[80:81], v[44:45], v[0:1] op_sel_hi:[1,0]
	v_pk_mul_f32 v[74:75], v[66:67], v[74:75]
	v_pk_mul_f32 v[76:77], v[68:69], v[76:77]
	v_pk_mul_f32 v[78:79], v[78:79], v[74:75]
	v_pk_mul_f32 v[80:81], v[80:81], v[76:77]
	v_cvt_pk_bf16_f32 v240, v78, v79
	v_cvt_pk_bf16_f32 v241, v80, v81
	s_waitcnt vmcnt(11)
	v_lshlrev_b32_e32 v66, 16, v100
	v_and_b32_e32 v67, 0xffff0000, v100
	v_lshlrev_b32_e32 v68, 16, v101
	v_and_b32_e32 v69, 0xffff0000, v101
	v_mul_f32_e32 v70, 0xbfb8aa3b, v66
	v_mul_f32_e32 v71, 0xbfb8aa3b, v67
	v_mul_f32_e32 v72, 0xbfb8aa3b, v68
	v_mul_f32_e32 v73, 0xbfb8aa3b, v69
	v_exp_f32_e32 v70, v70
	v_exp_f32_e32 v71, v71
	v_exp_f32_e32 v72, v72
	v_exp_f32_e32 v73, v73
	v_pk_mul_f32 v[78:79], v[38:39], v[0:1] op_sel_hi:[1,0]
	v_pk_add_f32 v[70:71], v[70:71], 1.0 op_sel_hi:[1,0]
	v_pk_add_f32 v[72:73], v[72:73], 1.0 op_sel_hi:[1,0]
	v_rcp_f32_e32 v74, v70
	v_rcp_f32_e32 v75, v71
	v_rcp_f32_e32 v76, v72
	v_rcp_f32_e32 v77, v73
	v_pk_mul_f32 v[80:81], v[40:41], v[0:1] op_sel_hi:[1,0]
	v_pk_mul_f32 v[74:75], v[66:67], v[74:75]
	v_pk_mul_f32 v[76:77], v[68:69], v[76:77]
	v_pk_mul_f32 v[78:79], v[78:79], v[74:75]
	v_pk_mul_f32 v[80:81], v[80:81], v[76:77]
	v_cvt_pk_bf16_f32 v242, v78, v79
	v_cvt_pk_bf16_f32 v243, v80, v81
	s_nop 1
	v_permlane16_swap_b32_e32 v240, v242
	v_permlane16_swap_b32_e32 v241, v243
	global_store_dwordx4 v244, v[240:243], s[38:39] offset:192
	s_waitcnt vmcnt(11)
	v_lshlrev_b32_e32 v66, 16, v102
	v_and_b32_e32 v67, 0xffff0000, v102
	v_lshlrev_b32_e32 v68, 16, v103
	v_and_b32_e32 v69, 0xffff0000, v103
	v_mul_f32_e32 v70, 0xbfb8aa3b, v66
	v_mul_f32_e32 v71, 0xbfb8aa3b, v67
	v_mul_f32_e32 v72, 0xbfb8aa3b, v68
	v_mul_f32_e32 v73, 0xbfb8aa3b, v69
	v_exp_f32_e32 v70, v70
	v_exp_f32_e32 v71, v71
	v_exp_f32_e32 v72, v72
	v_exp_f32_e32 v73, v73
	v_pk_mul_f32 v[78:79], v[30:31], v[120:121] op_sel_hi:[1,0]
	v_pk_add_f32 v[70:71], v[70:71], 1.0 op_sel_hi:[1,0]
	v_pk_add_f32 v[72:73], v[72:73], 1.0 op_sel_hi:[1,0]
	v_rcp_f32_e32 v74, v70
	v_rcp_f32_e32 v75, v71
	v_rcp_f32_e32 v76, v72
	v_rcp_f32_e32 v77, v73
	v_pk_mul_f32 v[80:81], v[32:33], v[120:121] op_sel_hi:[1,0]
	v_pk_mul_f32 v[74:75], v[66:67], v[74:75]
	v_pk_mul_f32 v[76:77], v[68:69], v[76:77]
	v_pk_mul_f32 v[78:79], v[78:79], v[74:75]
	v_pk_mul_f32 v[80:81], v[80:81], v[76:77]
	v_cvt_pk_bf16_f32 v240, v78, v79
	v_cvt_pk_bf16_f32 v241, v80, v81
	s_waitcnt vmcnt(10)
	v_lshlrev_b32_e32 v66, 16, v104
	v_and_b32_e32 v67, 0xffff0000, v104
	v_lshlrev_b32_e32 v68, 16, v105
	v_and_b32_e32 v69, 0xffff0000, v105
	v_mul_f32_e32 v70, 0xbfb8aa3b, v66
	v_mul_f32_e32 v71, 0xbfb8aa3b, v67
	v_mul_f32_e32 v72, 0xbfb8aa3b, v68
	v_mul_f32_e32 v73, 0xbfb8aa3b, v69
	v_exp_f32_e32 v70, v70
	v_exp_f32_e32 v71, v71
	v_exp_f32_e32 v72, v72
	v_exp_f32_e32 v73, v73
	v_pk_mul_f32 v[78:79], v[26:27], v[120:121] op_sel_hi:[1,0]
	v_pk_add_f32 v[70:71], v[70:71], 1.0 op_sel_hi:[1,0]
	v_pk_add_f32 v[72:73], v[72:73], 1.0 op_sel_hi:[1,0]
	v_rcp_f32_e32 v74, v70
	v_rcp_f32_e32 v75, v71
	v_rcp_f32_e32 v76, v72
	v_rcp_f32_e32 v77, v73
	v_pk_mul_f32 v[80:81], v[28:29], v[120:121] op_sel_hi:[1,0]
	v_pk_mul_f32 v[74:75], v[66:67], v[74:75]
	v_pk_mul_f32 v[76:77], v[68:69], v[76:77]
	v_pk_mul_f32 v[78:79], v[78:79], v[74:75]
	v_pk_mul_f32 v[80:81], v[80:81], v[76:77]
	v_cvt_pk_bf16_f32 v242, v78, v79
	v_cvt_pk_bf16_f32 v243, v80, v81
	s_nop 1
	v_permlane16_swap_b32_e32 v240, v242
	v_permlane16_swap_b32_e32 v241, v243
	global_store_dwordx4 v245, v[240:243], s[38:39]
	s_waitcnt vmcnt(10)
	v_lshlrev_b32_e32 v66, 16, v106
	v_and_b32_e32 v67, 0xffff0000, v106
	v_lshlrev_b32_e32 v68, 16, v107
	v_and_b32_e32 v69, 0xffff0000, v107
	v_mul_f32_e32 v70, 0xbfb8aa3b, v66
	v_mul_f32_e32 v71, 0xbfb8aa3b, v67
	v_mul_f32_e32 v72, 0xbfb8aa3b, v68
	v_mul_f32_e32 v73, 0xbfb8aa3b, v69
	v_exp_f32_e32 v70, v70
	v_exp_f32_e32 v71, v71
	v_exp_f32_e32 v72, v72
	v_exp_f32_e32 v73, v73
	v_pk_mul_f32 v[78:79], v[22:23], v[120:121] op_sel_hi:[1,0]
	v_pk_add_f32 v[70:71], v[70:71], 1.0 op_sel_hi:[1,0]
	v_pk_add_f32 v[72:73], v[72:73], 1.0 op_sel_hi:[1,0]
	v_rcp_f32_e32 v74, v70
	v_rcp_f32_e32 v75, v71
	v_rcp_f32_e32 v76, v72
	v_rcp_f32_e32 v77, v73
	v_pk_mul_f32 v[80:81], v[24:25], v[120:121] op_sel_hi:[1,0]
	v_pk_mul_f32 v[74:75], v[66:67], v[74:75]
	v_pk_mul_f32 v[76:77], v[68:69], v[76:77]
	v_pk_mul_f32 v[78:79], v[78:79], v[74:75]
	v_pk_mul_f32 v[80:81], v[80:81], v[76:77]
	v_cvt_pk_bf16_f32 v240, v78, v79
	v_cvt_pk_bf16_f32 v241, v80, v81
	s_waitcnt vmcnt(9)
	v_lshlrev_b32_e32 v66, 16, v108
	v_and_b32_e32 v67, 0xffff0000, v108
	v_lshlrev_b32_e32 v68, 16, v109
	v_and_b32_e32 v69, 0xffff0000, v109
	v_mul_f32_e32 v70, 0xbfb8aa3b, v66
	v_mul_f32_e32 v71, 0xbfb8aa3b, v67
	v_mul_f32_e32 v72, 0xbfb8aa3b, v68
	v_mul_f32_e32 v73, 0xbfb8aa3b, v69
	v_exp_f32_e32 v70, v70
	v_exp_f32_e32 v71, v71
	v_exp_f32_e32 v72, v72
	v_exp_f32_e32 v73, v73
	v_pk_mul_f32 v[78:79], v[18:19], v[120:121] op_sel_hi:[1,0]
	v_pk_add_f32 v[70:71], v[70:71], 1.0 op_sel_hi:[1,0]
	v_pk_add_f32 v[72:73], v[72:73], 1.0 op_sel_hi:[1,0]
	v_rcp_f32_e32 v74, v70
	v_rcp_f32_e32 v75, v71
	v_rcp_f32_e32 v76, v72
	v_rcp_f32_e32 v77, v73
	v_pk_mul_f32 v[80:81], v[20:21], v[120:121] op_sel_hi:[1,0]
	v_pk_mul_f32 v[74:75], v[66:67], v[74:75]
	v_pk_mul_f32 v[76:77], v[68:69], v[76:77]
	v_pk_mul_f32 v[78:79], v[78:79], v[74:75]
	v_pk_mul_f32 v[80:81], v[80:81], v[76:77]
	v_cvt_pk_bf16_f32 v242, v78, v79
	v_cvt_pk_bf16_f32 v243, v80, v81
	s_nop 1
	v_permlane16_swap_b32_e32 v240, v242
	v_permlane16_swap_b32_e32 v241, v243
	global_store_dwordx4 v245, v[240:243], s[38:39] offset:64
	s_waitcnt vmcnt(9)
	v_lshlrev_b32_e32 v66, 16, v110
	v_and_b32_e32 v67, 0xffff0000, v110
	v_lshlrev_b32_e32 v68, 16, v111
	v_and_b32_e32 v69, 0xffff0000, v111
	v_mul_f32_e32 v70, 0xbfb8aa3b, v66
	v_mul_f32_e32 v71, 0xbfb8aa3b, v67
	v_mul_f32_e32 v72, 0xbfb8aa3b, v68
	v_mul_f32_e32 v73, 0xbfb8aa3b, v69
	v_exp_f32_e32 v70, v70
	v_exp_f32_e32 v71, v71
	v_exp_f32_e32 v72, v72
	v_exp_f32_e32 v73, v73
	v_pk_mul_f32 v[78:79], v[14:15], v[120:121] op_sel_hi:[1,0]
	v_pk_add_f32 v[70:71], v[70:71], 1.0 op_sel_hi:[1,0]
	v_pk_add_f32 v[72:73], v[72:73], 1.0 op_sel_hi:[1,0]
	v_rcp_f32_e32 v74, v70
	v_rcp_f32_e32 v75, v71
	v_rcp_f32_e32 v76, v72
	v_rcp_f32_e32 v77, v73
	v_pk_mul_f32 v[80:81], v[16:17], v[120:121] op_sel_hi:[1,0]
	v_pk_mul_f32 v[74:75], v[66:67], v[74:75]
	v_pk_mul_f32 v[76:77], v[68:69], v[76:77]
	v_pk_mul_f32 v[78:79], v[78:79], v[74:75]
	v_pk_mul_f32 v[80:81], v[80:81], v[76:77]
	v_cvt_pk_bf16_f32 v240, v78, v79
	v_cvt_pk_bf16_f32 v241, v80, v81
	s_waitcnt vmcnt(8)
	v_lshlrev_b32_e32 v66, 16, v112
	v_and_b32_e32 v67, 0xffff0000, v112
	v_lshlrev_b32_e32 v68, 16, v113
	v_and_b32_e32 v69, 0xffff0000, v113
	v_mul_f32_e32 v70, 0xbfb8aa3b, v66
	v_mul_f32_e32 v71, 0xbfb8aa3b, v67
	v_mul_f32_e32 v72, 0xbfb8aa3b, v68
	v_mul_f32_e32 v73, 0xbfb8aa3b, v69
	v_exp_f32_e32 v70, v70
	v_exp_f32_e32 v71, v71
	v_exp_f32_e32 v72, v72
	v_exp_f32_e32 v73, v73
	v_pk_mul_f32 v[78:79], v[10:11], v[120:121] op_sel_hi:[1,0]
	v_pk_add_f32 v[70:71], v[70:71], 1.0 op_sel_hi:[1,0]
	v_pk_add_f32 v[72:73], v[72:73], 1.0 op_sel_hi:[1,0]
	v_rcp_f32_e32 v74, v70
	v_rcp_f32_e32 v75, v71
	v_rcp_f32_e32 v76, v72
	v_rcp_f32_e32 v77, v73
	v_pk_mul_f32 v[80:81], v[12:13], v[120:121] op_sel_hi:[1,0]
	v_pk_mul_f32 v[74:75], v[66:67], v[74:75]
	v_pk_mul_f32 v[76:77], v[68:69], v[76:77]
	v_pk_mul_f32 v[78:79], v[78:79], v[74:75]
	v_pk_mul_f32 v[80:81], v[80:81], v[76:77]
	v_cvt_pk_bf16_f32 v242, v78, v79
	v_cvt_pk_bf16_f32 v243, v80, v81
	s_nop 1
	v_permlane16_swap_b32_e32 v240, v242
	v_permlane16_swap_b32_e32 v241, v243
	global_store_dwordx4 v245, v[240:243], s[38:39] offset:128
	s_waitcnt vmcnt(8)
	v_lshlrev_b32_e32 v66, 16, v114
	v_and_b32_e32 v67, 0xffff0000, v114
	v_lshlrev_b32_e32 v68, 16, v115
	v_and_b32_e32 v69, 0xffff0000, v115
	v_mul_f32_e32 v70, 0xbfb8aa3b, v66
	v_mul_f32_e32 v71, 0xbfb8aa3b, v67
	v_mul_f32_e32 v72, 0xbfb8aa3b, v68
	v_mul_f32_e32 v73, 0xbfb8aa3b, v69
	v_exp_f32_e32 v70, v70
	v_exp_f32_e32 v71, v71
	v_exp_f32_e32 v72, v72
	v_exp_f32_e32 v73, v73
	v_pk_mul_f32 v[78:79], v[6:7], v[120:121] op_sel_hi:[1,0]
	v_pk_add_f32 v[70:71], v[70:71], 1.0 op_sel_hi:[1,0]
	v_pk_add_f32 v[72:73], v[72:73], 1.0 op_sel_hi:[1,0]
	v_rcp_f32_e32 v74, v70
	v_rcp_f32_e32 v75, v71
	v_rcp_f32_e32 v76, v72
	v_rcp_f32_e32 v77, v73
	v_pk_mul_f32 v[80:81], v[8:9], v[120:121] op_sel_hi:[1,0]
	v_pk_mul_f32 v[74:75], v[66:67], v[74:75]
	v_pk_mul_f32 v[76:77], v[68:69], v[76:77]
	v_pk_mul_f32 v[78:79], v[78:79], v[74:75]
	v_pk_mul_f32 v[80:81], v[80:81], v[76:77]
	v_cvt_pk_bf16_f32 v240, v78, v79
	v_cvt_pk_bf16_f32 v241, v80, v81
	s_waitcnt vmcnt(7)
	v_lshlrev_b32_e32 v66, 16, v116
	v_and_b32_e32 v67, 0xffff0000, v116
	v_lshlrev_b32_e32 v68, 16, v117
	v_and_b32_e32 v69, 0xffff0000, v117
	v_mul_f32_e32 v70, 0xbfb8aa3b, v66
	v_mul_f32_e32 v71, 0xbfb8aa3b, v67
	v_mul_f32_e32 v72, 0xbfb8aa3b, v68
	v_mul_f32_e32 v73, 0xbfb8aa3b, v69
	v_exp_f32_e32 v70, v70
	v_exp_f32_e32 v71, v71
	v_exp_f32_e32 v72, v72
	v_exp_f32_e32 v73, v73
	v_pk_mul_f32 v[78:79], v[2:3], v[120:121] op_sel_hi:[1,0]
	v_pk_add_f32 v[70:71], v[70:71], 1.0 op_sel_hi:[1,0]
	v_pk_add_f32 v[72:73], v[72:73], 1.0 op_sel_hi:[1,0]
	v_rcp_f32_e32 v74, v70
	v_rcp_f32_e32 v75, v71
	v_rcp_f32_e32 v76, v72
	v_rcp_f32_e32 v77, v73
	v_pk_mul_f32 v[80:81], v[4:5], v[120:121] op_sel_hi:[1,0]
	v_pk_mul_f32 v[74:75], v[66:67], v[74:75]
	v_pk_mul_f32 v[76:77], v[68:69], v[76:77]
	v_pk_mul_f32 v[78:79], v[78:79], v[74:75]
	v_pk_mul_f32 v[80:81], v[80:81], v[76:77]
	v_cvt_pk_bf16_f32 v242, v78, v79
	v_cvt_pk_bf16_f32 v243, v80, v81
	s_nop 1
	v_permlane16_swap_b32_e32 v240, v242
	v_permlane16_swap_b32_e32 v241, v243
	global_store_dwordx4 v245, v[240:243], s[38:39] offset:192
	v_readlane_b32 s0, v236, 9
	s_add_i32 s40, s40, s0
	v_readlane_b32 s1, v236, 10
	s_cmpk_gt_i32 s40, 0xff
	s_cbranch_scc1 .LBB0_401
